# skinny_stage (branch, GLU, pool sample-row staging): 8 serialized load+wait+LDS-write steps turned into 8 loads in flight then the LDS writes
# speedup vs baseline: 1.0108x; 1.0108x over previous
; #define LAS __attribute__((address_space(3)))
; template <int KP>
; __device__ __forceinline__ void skinny_stage(LAS unsigned char* lds, const bf16_t* A, int lda, int tid) {
;     constexpr int CH = KP / 8;
; #pragma unroll 8
;     for (int i = tid; i < 32 * CH; i += NT) { const int r = i / CH, c = i % CH; *(LAS u32x4*)(lds + r * (KP * 2 + 16) + c * 16) = *(const u32x4*)(A + (size_t)r * lda + 8 * c); }
;     __syncthreads();
.LBB0_1147:
	v_ashrrev_i32_e32 v5, 31, v2
	v_lshrrev_b32_e32 v5, 25, v5
	v_add_u32_e32 v5, v2, v5
	v_ashrrev_i32_e32 v26, 7, v5
	v_ashrrev_i32_e32 v27, 31, v26
	v_lshlrev_b32_e32 v5, 10, v26
	v_lshlrev_b64 v[140:141], 11, v[26:27]
	v_sub_u32_e32 v8, v3, v5
	v_lshl_add_u64 v[140:141], s[50:51], 0, v[140:141]
	v_ashrrev_i32_e32 v9, 31, v8
	v_lshl_add_u64 v[140:141], v[8:9], 1, v[140:141]
	global_load_dwordx4 v[100:103], v[140:141], off
	v_lshl_add_u32 v132, v26, 4, v4
	v_cmp_lt_i32_e32 vcc, -1, v2
	v_add_u32_e32 v3, 0x8000, v3
	v_add_u32_e32 v4, 0x10000, v4
	s_or_b64 s[54:55], vcc, s[54:55]
	v_add_u32_e32 v5, 0x200, v2
	v_ashrrev_i32_e32 v6, 31, v5
	v_lshrrev_b32_e32 v6, 25, v6
	v_add_u32_e32 v6, v5, v6
	v_ashrrev_i32_e32 v26, 7, v6
	v_and_b32_e32 v6, 0xffffff80, v6
	v_sub_u32_e32 v5, v5, v6
	v_ashrrev_i32_e32 v27, 31, v26
	v_lshlrev_b64 v[142:143], 11, v[26:27]
	v_lshlrev_b32_e32 v8, 3, v5
	v_lshl_add_u64 v[142:143], s[50:51], 0, v[142:143]
	v_ashrrev_i32_e32 v9, 31, v8
	v_lshl_add_u64 v[142:143], v[8:9], 1, v[142:143]
	global_load_dwordx4 v[104:107], v[142:143], off
	v_mul_lo_u32 v23, v26, s80
	v_lshlrev_b32_e32 v5, 4, v5
	v_add3_u32 v133, 0, v23, v5
	v_add_u32_e32 v5, 0x400, v2
	v_ashrrev_i32_e32 v6, 31, v5
	v_lshrrev_b32_e32 v6, 25, v6
	v_add_u32_e32 v6, v5, v6
	v_ashrrev_i32_e32 v26, 7, v6
	v_and_b32_e32 v6, 0xffffff80, v6
	v_sub_u32_e32 v5, v5, v6
	v_ashrrev_i32_e32 v27, 31, v26
	v_lshlrev_b64 v[144:145], 11, v[26:27]
	v_lshlrev_b32_e32 v8, 3, v5
	v_lshl_add_u64 v[144:145], s[50:51], 0, v[144:145]
	v_ashrrev_i32_e32 v9, 31, v8
	v_lshl_add_u64 v[144:145], v[8:9], 1, v[144:145]
	global_load_dwordx4 v[108:111], v[144:145], off
	v_mul_lo_u32 v23, v26, s80
	v_lshlrev_b32_e32 v5, 4, v5
	v_add3_u32 v134, 0, v23, v5
	v_add_u32_e32 v5, 0x600, v2
	v_ashrrev_i32_e32 v6, 31, v5
	v_lshrrev_b32_e32 v6, 25, v6
	v_add_u32_e32 v6, v5, v6
	v_ashrrev_i32_e32 v26, 7, v6
	v_and_b32_e32 v6, 0xffffff80, v6
	v_sub_u32_e32 v5, v5, v6
	v_ashrrev_i32_e32 v27, 31, v26
	v_lshlrev_b64 v[146:147], 11, v[26:27]
	v_lshlrev_b32_e32 v8, 3, v5
	v_lshl_add_u64 v[146:147], s[50:51], 0, v[146:147]
	v_ashrrev_i32_e32 v9, 31, v8
	v_lshl_add_u64 v[146:147], v[8:9], 1, v[146:147]
	global_load_dwordx4 v[112:115], v[146:147], off
	v_mul_lo_u32 v23, v26, s80
	v_lshlrev_b32_e32 v5, 4, v5
	v_add3_u32 v135, 0, v23, v5
	v_add_u32_e32 v5, 0x800, v2
	v_ashrrev_i32_e32 v6, 31, v5
	v_lshrrev_b32_e32 v6, 25, v6
	v_add_u32_e32 v6, v5, v6
	v_ashrrev_i32_e32 v26, 7, v6
	v_and_b32_e32 v6, 0xffffff80, v6
	v_sub_u32_e32 v5, v5, v6
	v_ashrrev_i32_e32 v27, 31, v26
	v_lshlrev_b64 v[148:149], 11, v[26:27]
	v_lshlrev_b32_e32 v8, 3, v5
	v_lshl_add_u64 v[148:149], s[50:51], 0, v[148:149]
	v_ashrrev_i32_e32 v9, 31, v8
	v_lshl_add_u64 v[148:149], v[8:9], 1, v[148:149]
	global_load_dwordx4 v[116:119], v[148:149], off
	v_mul_lo_u32 v23, v26, s80
	v_lshlrev_b32_e32 v5, 4, v5
	v_add3_u32 v136, 0, v23, v5
	v_add_u32_e32 v5, 0xa00, v2
	v_ashrrev_i32_e32 v6, 31, v5
	v_lshrrev_b32_e32 v6, 25, v6
	v_add_u32_e32 v6, v5, v6
	v_ashrrev_i32_e32 v26, 7, v6
	v_and_b32_e32 v6, 0xffffff80, v6
	v_sub_u32_e32 v5, v5, v6
	v_ashrrev_i32_e32 v27, 31, v26
	v_lshlrev_b64 v[150:151], 11, v[26:27]
	v_lshlrev_b32_e32 v8, 3, v5
	v_lshl_add_u64 v[150:151], s[50:51], 0, v[150:151]
	v_ashrrev_i32_e32 v9, 31, v8
	v_lshl_add_u64 v[150:151], v[8:9], 1, v[150:151]
	global_load_dwordx4 v[120:123], v[150:151], off
	v_mul_lo_u32 v23, v26, s80
	v_lshlrev_b32_e32 v5, 4, v5
	v_add3_u32 v137, 0, v23, v5
	v_add_u32_e32 v5, 0xc00, v2
	v_ashrrev_i32_e32 v6, 31, v5
	v_lshrrev_b32_e32 v6, 25, v6
	v_add_u32_e32 v6, v5, v6
	v_ashrrev_i32_e32 v26, 7, v6
	v_and_b32_e32 v6, 0xffffff80, v6
	v_sub_u32_e32 v5, v5, v6
	v_ashrrev_i32_e32 v27, 31, v26
	v_lshlrev_b64 v[152:153], 11, v[26:27]
	v_lshlrev_b32_e32 v8, 3, v5
	v_lshl_add_u64 v[152:153], s[50:51], 0, v[152:153]
	v_ashrrev_i32_e32 v9, 31, v8
	v_lshl_add_u64 v[152:153], v[8:9], 1, v[152:153]
	global_load_dwordx4 v[124:127], v[152:153], off
	v_mul_lo_u32 v23, v26, s80
	v_lshlrev_b32_e32 v5, 4, v5
	v_add3_u32 v138, 0, v23, v5
	v_add_u32_e32 v5, 0xe00, v2
	v_ashrrev_i32_e32 v6, 31, v5
	v_lshrrev_b32_e32 v6, 25, v6
	v_add_u32_e32 v6, v5, v6
	v_ashrrev_i32_e32 v26, 7, v6
	v_and_b32_e32 v6, 0xffffff80, v6
	v_sub_u32_e32 v5, v5, v6
	v_ashrrev_i32_e32 v27, 31, v26
	v_lshlrev_b64 v[154:155], 11, v[26:27]
	v_lshlrev_b32_e32 v8, 3, v5
	v_lshl_add_u64 v[154:155], s[50:51], 0, v[154:155]
	v_ashrrev_i32_e32 v9, 31, v8
	v_lshl_add_u64 v[154:155], v[8:9], 1, v[154:155]
	global_load_dwordx4 v[128:131], v[154:155], off
	v_mul_lo_u32 v23, v26, s80
	v_lshlrev_b32_e32 v5, 4, v5
	v_add3_u32 v139, 0, v23, v5
	v_add_u32_e32 v2, 0x1000, v2
	s_waitcnt vmcnt(7)
	ds_write_b128 v132, v[100:103]
	s_waitcnt vmcnt(6)
	ds_write_b128 v133, v[104:107]
	s_waitcnt vmcnt(5)
	ds_write_b128 v134, v[108:111]
	s_waitcnt vmcnt(4)
	ds_write_b128 v135, v[112:115]
	s_waitcnt vmcnt(3)
	ds_write_b128 v136, v[116:119]
	s_waitcnt vmcnt(2)
	ds_write_b128 v137, v[120:123]
	s_waitcnt vmcnt(1)
	ds_write_b128 v138, v[124:127]
	s_waitcnt vmcnt(0)
	ds_write_b128 v139, v[128:131]
	s_andn2_b64 exec, exec, s[54:55]
	s_cbranch_execnz .LBB0_1147

; #define LAS __attribute__((address_space(3)))
; template <int KP>
; __device__ __forceinline__ void skinny_stage(LAS unsigned char* lds, const bf16_t* A, int lda, int tid) {
;     constexpr int CH = KP / 8;
; #pragma unroll 8
;     for (int i = tid; i < 32 * CH; i += NT) { const int r = i / CH, c = i % CH; *(LAS u32x4*)(lds + r * (KP * 2 + 16) + c * 16) = *(const u32x4*)(A + (size_t)r * lda + 8 * c); }
;     __syncthreads();
.LBB0_1164:
	v_ashrrev_i32_e32 v5, 31, v2
	v_lshrrev_b32_e32 v5, 25, v5
	v_add_u32_e32 v5, v2, v5
	v_ashrrev_i32_e32 v22, 7, v5
	v_ashrrev_i32_e32 v23, 31, v22
	v_lshlrev_b32_e32 v5, 10, v22
	v_lshlrev_b64 v[140:141], 11, v[22:23]
	v_sub_u32_e32 v20, v3, v5
	v_lshl_add_u64 v[140:141], s[18:19], 0, v[140:141]
	v_ashrrev_i32_e32 v21, 31, v20
	v_lshl_add_u64 v[140:141], v[20:21], 1, v[140:141]
	global_load_dwordx4 v[100:103], v[140:141], off
	v_lshl_add_u32 v132, v22, 4, v4
	v_cmp_lt_i32_e32 vcc, -1, v2
	v_add_u32_e32 v3, 0x8000, v3
	v_add_u32_e32 v4, 0x10000, v4
	s_or_b64 s[50:51], vcc, s[50:51]
	v_add_u32_e32 v5, 0x200, v2
	v_ashrrev_i32_e32 v17, 31, v5
	v_lshrrev_b32_e32 v17, 25, v17
	v_add_u32_e32 v17, v5, v17
	v_ashrrev_i32_e32 v22, 7, v17
	v_and_b32_e32 v17, 0xffffff80, v17
	v_sub_u32_e32 v5, v5, v17
	v_ashrrev_i32_e32 v23, 31, v22
	v_lshlrev_b64 v[142:143], 11, v[22:23]
	v_lshlrev_b32_e32 v20, 3, v5
	v_lshl_add_u64 v[142:143], s[18:19], 0, v[142:143]
	v_ashrrev_i32_e32 v21, 31, v20
	v_lshl_add_u64 v[142:143], v[20:21], 1, v[142:143]
	global_load_dwordx4 v[104:107], v[142:143], off
	v_mul_lo_u32 v17, v22, s80
	v_lshlrev_b32_e32 v5, 4, v5
	v_add3_u32 v133, 0, v17, v5
	v_add_u32_e32 v5, 0x400, v2
	v_ashrrev_i32_e32 v17, 31, v5
	v_lshrrev_b32_e32 v17, 25, v17
	v_add_u32_e32 v17, v5, v17
	v_ashrrev_i32_e32 v22, 7, v17
	v_and_b32_e32 v17, 0xffffff80, v17
	v_sub_u32_e32 v5, v5, v17
	v_ashrrev_i32_e32 v23, 31, v22
	v_lshlrev_b64 v[144:145], 11, v[22:23]
	v_lshlrev_b32_e32 v20, 3, v5
	v_lshl_add_u64 v[144:145], s[18:19], 0, v[144:145]
	v_ashrrev_i32_e32 v21, 31, v20
	v_lshl_add_u64 v[144:145], v[20:21], 1, v[144:145]
	global_load_dwordx4 v[108:111], v[144:145], off
	v_mul_lo_u32 v17, v22, s80
	v_lshlrev_b32_e32 v5, 4, v5
	v_add3_u32 v134, 0, v17, v5
	v_add_u32_e32 v5, 0x600, v2
	v_ashrrev_i32_e32 v17, 31, v5
	v_lshrrev_b32_e32 v17, 25, v17
	v_add_u32_e32 v17, v5, v17
	v_ashrrev_i32_e32 v22, 7, v17
	v_and_b32_e32 v17, 0xffffff80, v17
	v_sub_u32_e32 v5, v5, v17
	v_ashrrev_i32_e32 v23, 31, v22
	v_lshlrev_b64 v[146:147], 11, v[22:23]
	v_lshlrev_b32_e32 v20, 3, v5
	v_lshl_add_u64 v[146:147], s[18:19], 0, v[146:147]
	v_ashrrev_i32_e32 v21, 31, v20
	v_lshl_add_u64 v[146:147], v[20:21], 1, v[146:147]
	global_load_dwordx4 v[112:115], v[146:147], off
	v_mul_lo_u32 v17, v22, s80
	v_lshlrev_b32_e32 v5, 4, v5
	v_add3_u32 v135, 0, v17, v5
	v_add_u32_e32 v5, 0x800, v2
	v_ashrrev_i32_e32 v17, 31, v5
	v_lshrrev_b32_e32 v17, 25, v17
	v_add_u32_e32 v17, v5, v17
	v_ashrrev_i32_e32 v22, 7, v17
	v_and_b32_e32 v17, 0xffffff80, v17
	v_sub_u32_e32 v5, v5, v17
	v_ashrrev_i32_e32 v23, 31, v22
	v_lshlrev_b64 v[148:149], 11, v[22:23]
	v_lshlrev_b32_e32 v20, 3, v5
	v_lshl_add_u64 v[148:149], s[18:19], 0, v[148:149]
	v_ashrrev_i32_e32 v21, 31, v20
	v_lshl_add_u64 v[148:149], v[20:21], 1, v[148:149]
	global_load_dwordx4 v[116:119], v[148:149], off
	v_mul_lo_u32 v17, v22, s80
	v_lshlrev_b32_e32 v5, 4, v5
	v_add3_u32 v136, 0, v17, v5
	v_add_u32_e32 v5, 0xa00, v2
	v_ashrrev_i32_e32 v17, 31, v5
	v_lshrrev_b32_e32 v17, 25, v17
	v_add_u32_e32 v17, v5, v17
	v_ashrrev_i32_e32 v22, 7, v17
	v_and_b32_e32 v17, 0xffffff80, v17
	v_sub_u32_e32 v5, v5, v17
	v_ashrrev_i32_e32 v23, 31, v22
	v_lshlrev_b64 v[150:151], 11, v[22:23]
	v_lshlrev_b32_e32 v20, 3, v5
	v_lshl_add_u64 v[150:151], s[18:19], 0, v[150:151]
	v_ashrrev_i32_e32 v21, 31, v20
	v_lshl_add_u64 v[150:151], v[20:21], 1, v[150:151]
	global_load_dwordx4 v[120:123], v[150:151], off
	v_mul_lo_u32 v17, v22, s80
	v_lshlrev_b32_e32 v5, 4, v5
	v_add3_u32 v137, 0, v17, v5
	v_add_u32_e32 v5, 0xc00, v2
	v_ashrrev_i32_e32 v17, 31, v5
	v_lshrrev_b32_e32 v17, 25, v17
	v_add_u32_e32 v17, v5, v17
	v_ashrrev_i32_e32 v22, 7, v17
	v_and_b32_e32 v17, 0xffffff80, v17
	v_sub_u32_e32 v5, v5, v17
	v_ashrrev_i32_e32 v23, 31, v22
	v_lshlrev_b64 v[152:153], 11, v[22:23]
	v_lshlrev_b32_e32 v20, 3, v5
	v_lshl_add_u64 v[152:153], s[18:19], 0, v[152:153]
	v_ashrrev_i32_e32 v21, 31, v20
	v_lshl_add_u64 v[152:153], v[20:21], 1, v[152:153]
	global_load_dwordx4 v[124:127], v[152:153], off
	v_mul_lo_u32 v17, v22, s80
	v_lshlrev_b32_e32 v5, 4, v5
	v_add3_u32 v138, 0, v17, v5
	v_add_u32_e32 v5, 0xe00, v2
	v_ashrrev_i32_e32 v17, 31, v5
	v_lshrrev_b32_e32 v17, 25, v17
	v_add_u32_e32 v17, v5, v17
	v_ashrrev_i32_e32 v22, 7, v17
	v_and_b32_e32 v17, 0xffffff80, v17
	v_sub_u32_e32 v5, v5, v17
	v_ashrrev_i32_e32 v23, 31, v22
	v_lshlrev_b64 v[154:155], 11, v[22:23]
	v_lshlrev_b32_e32 v20, 3, v5
	v_lshl_add_u64 v[154:155], s[18:19], 0, v[154:155]
	v_ashrrev_i32_e32 v21, 31, v20
	v_lshl_add_u64 v[154:155], v[20:21], 1, v[154:155]
	global_load_dwordx4 v[128:131], v[154:155], off
	v_mul_lo_u32 v17, v22, s80
	v_lshlrev_b32_e32 v5, 4, v5
	v_add3_u32 v139, 0, v17, v5
	v_add_u32_e32 v2, 0x1000, v2
	s_waitcnt vmcnt(7)
	ds_write_b128 v132, v[100:103]
	s_waitcnt vmcnt(6)
	ds_write_b128 v133, v[104:107]
	s_waitcnt vmcnt(5)
	ds_write_b128 v134, v[108:111]
	s_waitcnt vmcnt(4)
	ds_write_b128 v135, v[112:115]
	s_waitcnt vmcnt(3)
	ds_write_b128 v136, v[116:119]
	s_waitcnt vmcnt(2)
	ds_write_b128 v137, v[120:123]
	s_waitcnt vmcnt(1)
	ds_write_b128 v138, v[124:127]
	s_waitcnt vmcnt(0)
	ds_write_b128 v139, v[128:131]
	s_andn2_b64 exec, exec, s[50:51]
	s_cbranch_execnz .LBB0_1164
	s_branch .LBB0_1154

; #define LAS __attribute__((address_space(3)))
; template <int KP>
; __device__ __forceinline__ void skinny_stage(LAS unsigned char* lds, const bf16_t* A, int lda, int tid) {
;     constexpr int CH = KP / 8;
; #pragma unroll 8
;     for (int i = tid; i < 32 * CH; i += NT) { const int r = i / CH, c = i % CH; *(LAS u32x4*)(lds + r * (KP * 2 + 16) + c * 16) = *(const u32x4*)(A + (size_t)r * lda + 8 * c); }
;     __syncthreads();
.LBB0_1321:
	v_ashrrev_i32_e32 v5, 31, v2
	v_lshrrev_b32_e32 v5, 25, v5
	v_add_u32_e32 v5, v2, v5
	v_ashrrev_i32_e32 v34, 7, v5
	v_ashrrev_i32_e32 v35, 31, v34
	v_lshlrev_b32_e32 v5, 10, v34
	v_lshlrev_b64 v[140:141], 11, v[34:35]
	v_sub_u32_e32 v8, v3, v5
	v_lshl_add_u64 v[140:141], s[54:55], 0, v[140:141]
	v_ashrrev_i32_e32 v9, 31, v8
	v_lshl_add_u64 v[140:141], v[8:9], 1, v[140:141]
	global_load_dwordx4 v[100:103], v[140:141], off
	v_lshl_add_u32 v132, v34, 4, v4
	v_cmp_lt_i32_e32 vcc, -1, v2
	v_add_u32_e32 v3, 0x8000, v3
	v_add_u32_e32 v4, 0x10000, v4
	s_or_b64 s[56:57], vcc, s[56:57]
	v_add_u32_e32 v5, 0x200, v2
	v_ashrrev_i32_e32 v6, 31, v5
	v_lshrrev_b32_e32 v6, 25, v6
	v_add_u32_e32 v6, v5, v6
	v_ashrrev_i32_e32 v34, 7, v6
	v_and_b32_e32 v6, 0xffffff80, v6
	v_sub_u32_e32 v5, v5, v6
	v_ashrrev_i32_e32 v35, 31, v34
	v_lshlrev_b64 v[142:143], 11, v[34:35]
	v_lshlrev_b32_e32 v8, 3, v5
	v_lshl_add_u64 v[142:143], s[54:55], 0, v[142:143]
	v_ashrrev_i32_e32 v9, 31, v8
	v_lshl_add_u64 v[142:143], v[8:9], 1, v[142:143]
	global_load_dwordx4 v[104:107], v[142:143], off
	v_mul_lo_u32 v27, v34, s80
	v_lshlrev_b32_e32 v5, 4, v5
	v_add3_u32 v133, 0, v27, v5
	v_add_u32_e32 v5, 0x400, v2
	v_ashrrev_i32_e32 v6, 31, v5
	v_lshrrev_b32_e32 v6, 25, v6
	v_add_u32_e32 v6, v5, v6
	v_ashrrev_i32_e32 v34, 7, v6
	v_and_b32_e32 v6, 0xffffff80, v6
	v_sub_u32_e32 v5, v5, v6
	v_ashrrev_i32_e32 v35, 31, v34
	v_lshlrev_b64 v[144:145], 11, v[34:35]
	v_lshlrev_b32_e32 v8, 3, v5
	v_lshl_add_u64 v[144:145], s[54:55], 0, v[144:145]
	v_ashrrev_i32_e32 v9, 31, v8
	v_lshl_add_u64 v[144:145], v[8:9], 1, v[144:145]
	global_load_dwordx4 v[108:111], v[144:145], off
	v_mul_lo_u32 v27, v34, s80
	v_lshlrev_b32_e32 v5, 4, v5
	v_add3_u32 v134, 0, v27, v5
	v_add_u32_e32 v5, 0x600, v2
	v_ashrrev_i32_e32 v6, 31, v5
	v_lshrrev_b32_e32 v6, 25, v6
	v_add_u32_e32 v6, v5, v6
	v_ashrrev_i32_e32 v34, 7, v6
	v_and_b32_e32 v6, 0xffffff80, v6
	v_sub_u32_e32 v5, v5, v6
	v_ashrrev_i32_e32 v35, 31, v34
	v_lshlrev_b64 v[146:147], 11, v[34:35]
	v_lshlrev_b32_e32 v8, 3, v5
	v_lshl_add_u64 v[146:147], s[54:55], 0, v[146:147]
	v_ashrrev_i32_e32 v9, 31, v8
	v_lshl_add_u64 v[146:147], v[8:9], 1, v[146:147]
	global_load_dwordx4 v[112:115], v[146:147], off
	v_mul_lo_u32 v27, v34, s80
	v_lshlrev_b32_e32 v5, 4, v5
	v_add3_u32 v135, 0, v27, v5
	v_add_u32_e32 v5, 0x800, v2
	v_ashrrev_i32_e32 v6, 31, v5
	v_lshrrev_b32_e32 v6, 25, v6
	v_add_u32_e32 v6, v5, v6
	v_ashrrev_i32_e32 v34, 7, v6
	v_and_b32_e32 v6, 0xffffff80, v6
	v_sub_u32_e32 v5, v5, v6
	v_ashrrev_i32_e32 v35, 31, v34
	v_lshlrev_b64 v[148:149], 11, v[34:35]
	v_lshlrev_b32_e32 v8, 3, v5
	v_lshl_add_u64 v[148:149], s[54:55], 0, v[148:149]
	v_ashrrev_i32_e32 v9, 31, v8
	v_lshl_add_u64 v[148:149], v[8:9], 1, v[148:149]
	global_load_dwordx4 v[116:119], v[148:149], off
	v_mul_lo_u32 v27, v34, s80
	v_lshlrev_b32_e32 v5, 4, v5
	v_add3_u32 v136, 0, v27, v5
	v_add_u32_e32 v5, 0xa00, v2
	v_ashrrev_i32_e32 v6, 31, v5
	v_lshrrev_b32_e32 v6, 25, v6
	v_add_u32_e32 v6, v5, v6
	v_ashrrev_i32_e32 v34, 7, v6
	v_and_b32_e32 v6, 0xffffff80, v6
	v_sub_u32_e32 v5, v5, v6
	v_ashrrev_i32_e32 v35, 31, v34
	v_lshlrev_b64 v[150:151], 11, v[34:35]
	v_lshlrev_b32_e32 v8, 3, v5
	v_lshl_add_u64 v[150:151], s[54:55], 0, v[150:151]
	v_ashrrev_i32_e32 v9, 31, v8
	v_lshl_add_u64 v[150:151], v[8:9], 1, v[150:151]
	global_load_dwordx4 v[120:123], v[150:151], off
	v_mul_lo_u32 v27, v34, s80
	v_lshlrev_b32_e32 v5, 4, v5
	v_add3_u32 v137, 0, v27, v5
	v_add_u32_e32 v5, 0xc00, v2
	v_ashrrev_i32_e32 v6, 31, v5
	v_lshrrev_b32_e32 v6, 25, v6
	v_add_u32_e32 v6, v5, v6
	v_ashrrev_i32_e32 v34, 7, v6
	v_and_b32_e32 v6, 0xffffff80, v6
	v_sub_u32_e32 v5, v5, v6
	v_ashrrev_i32_e32 v35, 31, v34
	v_lshlrev_b64 v[152:153], 11, v[34:35]
	v_lshlrev_b32_e32 v8, 3, v5
	v_lshl_add_u64 v[152:153], s[54:55], 0, v[152:153]
	v_ashrrev_i32_e32 v9, 31, v8
	v_lshl_add_u64 v[152:153], v[8:9], 1, v[152:153]
	global_load_dwordx4 v[124:127], v[152:153], off
	v_mul_lo_u32 v27, v34, s80
	v_lshlrev_b32_e32 v5, 4, v5
	v_add3_u32 v138, 0, v27, v5
	v_add_u32_e32 v5, 0xe00, v2
	v_ashrrev_i32_e32 v6, 31, v5
	v_lshrrev_b32_e32 v6, 25, v6
	v_add_u32_e32 v6, v5, v6
	v_ashrrev_i32_e32 v34, 7, v6
	v_and_b32_e32 v6, 0xffffff80, v6
	v_sub_u32_e32 v5, v5, v6
	v_ashrrev_i32_e32 v35, 31, v34
	v_lshlrev_b64 v[154:155], 11, v[34:35]
	v_lshlrev_b32_e32 v8, 3, v5
	v_lshl_add_u64 v[154:155], s[54:55], 0, v[154:155]
	v_ashrrev_i32_e32 v9, 31, v8
	v_lshl_add_u64 v[154:155], v[8:9], 1, v[154:155]
	global_load_dwordx4 v[128:131], v[154:155], off
	v_mul_lo_u32 v27, v34, s80
	v_lshlrev_b32_e32 v5, 4, v5
	v_add3_u32 v139, 0, v27, v5
	v_add_u32_e32 v2, 0x1000, v2
	s_waitcnt vmcnt(7)
	ds_write_b128 v132, v[100:103]
	s_waitcnt vmcnt(6)
	ds_write_b128 v133, v[104:107]
	s_waitcnt vmcnt(5)
	ds_write_b128 v134, v[108:111]
	s_waitcnt vmcnt(4)
	ds_write_b128 v135, v[112:115]
	s_waitcnt vmcnt(3)
	ds_write_b128 v136, v[116:119]
	s_waitcnt vmcnt(2)
	ds_write_b128 v137, v[120:123]
	s_waitcnt vmcnt(1)
	ds_write_b128 v138, v[124:127]
	s_waitcnt vmcnt(0)
	ds_write_b128 v139, v[128:131]
	s_andn2_b64 exec, exec, s[56:57]
	s_cbranch_execnz .LBB0_1321
